# SGU phase: LayerNorm gamma/beta loads of all four column batches issued at the top of each group iteration, u/W_s loads issued before the first wait (counted vmcnt)
# baseline (speedup 1.0000x reference)
; #define LAS __attribute__((address_space(3)))
; __device__ __forceinline__ unsigned pk_bf16(float lo, float hi) { unsigned r; asm volatile("v_cvt_pk_bf16_f32 %0, %1, %2" : "=v"(r) : "v"(lo), "v"(hi)); return r; }
; __device__ __forceinline__ float bf_lo(unsigned w) { return __uint_as_float(w << 16); }
; __device__ __forceinline__ float bf_hi(unsigned w) { return __uint_as_float(w & 0xffff0000u); }
; __device__ __forceinline__ void sgu_phase(LAS unsigned char* lds, const bf16* __restrict__ U, const bf16* __restrict__ V, bf16* __restrict__ Y, const bf16* __restrict__ Wm, ...
;     ...
;             for (int ks = 0; ks < 4; ++ks) af[ks] = *(const bf16x8*)(Wm + ((size_t)(g * 128 + tq) * 128 + ks * 32 + 8 * (lane >> 4)));
; #pragma unroll
;             for (int n = 0; n < 8; ++n) uw[n] = *(const u32x2*)(U + rowoff + g * 128 + n * 16 + 4 * (lane >> 4));
;             const float bs = b_s[g * 128 + tq];
;             {   const float mean = st[2 * srow], rstd = st[2 * srow + 1];
; #pragma unroll
;                 for (int i = 0; i < 4; ++i) { const int cc = (lane >> 4) + 4 * i, col = g * 128 + cc * 8; const u32x4 w = vr[i];
;                     const f32x4 g0 = *(const f32x4*)(ln_g + col), g1 = *(const f32x4*)(ln_g + col + 4), b0 = *(const f32x4*)(ln_b + col), b1 = *(const f32x4*)(ln_b + col + 4);
;                     LAS bf16* vt = VT + (cc * 8) * VTP + srow;
;                     vt[0 * VTP] = (bf16)pk_bf16((bf_lo(w.x) - mean) * rstd * g0.x + b0.x, 0.f); vt[1 * VTP] = (bf16)pk_bf16((bf_hi(w.x) - mean) * rstd * g0.y + b0.y, 0.f);
;                     vt[2 * VTP] = (bf16)pk_bf16((bf_lo(w.y) - mean) * rstd * g0.z + b0.z, 0.f); vt[3 * VTP] = (bf16)pk_bf16((bf_hi(w.y) - mean) * rstd * g0.w + b0.w, 0.f);
;                     vt[4 * VTP] = (bf16)pk_bf16((bf_lo(w.z) - mean) * rstd * g1.x + b1.x, 0.f); vt[5 * VTP] = (bf16)pk_bf16((bf_hi(w.z) - mean) * rstd * g1.y + b1.y, 0.f);
;                     vt[6 * VTP] = (bf16)pk_bf16((bf_lo(w.w) - mean) * rstd * g1.z + b1.z, 0.f); vt[7 * VTP] = (bf16)pk_bf16((bf_hi(w.w) - mean) * rstd * g1.w + b1.w, 0.f); } }
.LBB0_274:
	v_lshl_add_u64 v[24:25], s[36:37], 0, v[70:71]
	v_lshl_add_u64 v[22:23], s[34:35], 0, v[70:71]
	global_load_dwordx4 v[26:29], v[24:25], off
	global_load_dwordx4 v[30:33], v[22:23], off
	global_load_dwordx4 v[34:37], v[22:23], off offset:16
	global_load_dwordx4 v[44:47], v[24:25], off offset:16
	global_load_dwordx4 v[196:199], v[24:25], off offset:128
	global_load_dwordx4 v[200:203], v[22:23], off offset:128
	global_load_dwordx4 v[204:207], v[22:23], off offset:144
	global_load_dwordx4 v[208:211], v[24:25], off offset:144
	global_load_dwordx4 v[212:215], v[24:25], off offset:256
	global_load_dwordx4 v[216:219], v[22:23], off offset:256
	global_load_dwordx4 v[220:223], v[22:23], off offset:272
	global_load_dwordx4 v[224:227], v[24:25], off offset:272
	global_load_dwordx4 v[228:231], v[24:25], off offset:384
	global_load_dwordx4 v[232:235], v[22:23], off offset:384
	global_load_dwordx4 v[236:239], v[22:23], off offset:400
	global_load_dwordx4 v[240:243], v[24:25], off offset:400
	ds_read_b64 v[20:21], v74
	v_ashrrev_i32_e32 v85, 31, v84
	v_lshl_add_u64 v[16:17], v[88:89], 0, s[8:9]
	v_lshlrev_b64 v[18:19], 8, v[84:85]
	v_add_co_u32_e32 v16, vcc, s57, v16
	v_lshl_add_u64 v[38:39], v[84:85], 2, s[16:17]
	v_lshl_add_u64 v[18:19], v[72:73], 0, v[18:19]
	v_addc_co_u32_e32 v17, vcc, 0, v17, vcc
	global_load_dwordx2 v[104:105], v[16:17], off
	global_load_dwordx2 v[102:103], v[16:17], off offset:32
	global_load_dwordx2 v[100:101], v[16:17], off offset:64
	global_load_dwordx2 v[98:99], v[16:17], off offset:96
	global_load_dwordx2 v[96:97], v[16:17], off offset:128
	global_load_dwordx2 v[94:95], v[16:17], off offset:160
	global_load_dwordx2 v[92:93], v[16:17], off offset:192
	global_load_dwordx2 v[90:91], v[16:17], off offset:224
	global_load_dword v85, v[38:39], off
	global_load_dwordx4 v[60:63], v[18:19], off
	global_load_dwordx4 v[56:59], v[18:19], off offset:64
	global_load_dwordx4 v[40:43], v[18:19], off offset:128
	s_nop 0
	global_load_dwordx4 v[16:19], v[18:19], off offset:192
	s_waitcnt vmcnt(13) lgkmcnt(0)
	v_lshlrev_b32_e32 v48, 16, v0
	v_sub_f32_e32 v38, v48, v20
	v_and_b32_e32 v49, 0xffff0000, v0
	v_mul_f32_e32 v38, v21, v38
	v_lshlrev_b32_e32 v50, 16, v1
	v_sub_f32_e32 v39, v49, v20
	v_and_b32_e32 v51, 0xffff0000, v1
	v_sub_f32_e32 v48, v50, v20
	v_mul_f32_e32 v39, v21, v39
	v_lshlrev_b32_e32 v52, 16, v2
	v_sub_f32_e32 v49, v51, v20
	v_mul_f32_e32 v48, v21, v48
	v_and_b32_e32 v53, 0xffff0000, v2
	v_sub_f32_e32 v50, v52, v20
	v_mul_f32_e32 v49, v21, v49
	v_lshlrev_b32_e32 v54, 16, v3
	v_and_b32_e32 v55, 0xffff0000, v3
	v_sub_f32_e32 v51, v53, v20
	v_mul_f32_e32 v50, v21, v50
	v_sub_f32_e32 v52, v54, v20
	v_sub_f32_e32 v53, v55, v20
	v_mul_f32_e32 v51, v21, v51
	v_mul_f32_e32 v52, v21, v52
	v_mul_f32_e32 v53, v21, v53
	v_and_b32_e32 v54, 0xffff0000, v7
	v_sub_f32_e32 v54, v54, v20
	v_mul_f32_e32 v54, v21, v54
	s_cmpk_eq_i32 s8, 0x700
	v_fma_f32 v26, v38, v30, v26
	v_cvt_pk_bf16_f32 v26, v26, v71
	v_fma_f32 v27, v39, v31, v27
	ds_write_b16 v113, v26 offset:1024
	v_cvt_pk_bf16_f32 v26, v27, v71
	v_fma_f32 v28, v48, v32, v28
	ds_write_b16 v113, v26 offset:1296
	v_cvt_pk_bf16_f32 v26, v28, v71
	v_fmac_f32_e32 v29, v49, v33
	ds_write_b16 v113, v26 offset:1568
	v_cvt_pk_bf16_f32 v26, v29, v71
	v_fma_f32 v30, v50, v34, v44
	ds_write_b16 v113, v26 offset:1840
	v_cvt_pk_bf16_f32 v26, v30, v71
	v_fma_f32 v31, v51, v35, v45
	ds_write_b16 v113, v26 offset:2112
	v_cvt_pk_bf16_f32 v26, v31, v71
	v_fma_f32 v32, v52, v36, v46
	v_fmac_f32_e32 v47, v53, v37
	ds_write_b16 v113, v26 offset:2384
	v_cvt_pk_bf16_f32 v26, v32, v71
	ds_write_b16 v113, v26 offset:2656
	v_cvt_pk_bf16_f32 v38, v47, v71
	v_lshlrev_b32_e32 v39, 16, v4
	v_sub_f32_e32 v39, v39, v20
	v_and_b32_e32 v48, 0xffff0000, v4
	v_mul_f32_e32 v39, v21, v39
	v_lshlrev_b32_e32 v49, 16, v5
	v_sub_f32_e32 v48, v48, v20
	v_and_b32_e32 v50, 0xffff0000, v5
	v_sub_f32_e32 v49, v49, v20
	v_mul_f32_e32 v48, v21, v48
	ds_write_b16 v113, v38 offset:2928
	v_lshlrev_b32_e32 v51, 16, v6
	v_sub_f32_e32 v50, v50, v20
	v_mul_f32_e32 v49, v21, v49
	v_and_b32_e32 v52, 0xffff0000, v6
	v_sub_f32_e32 v51, v51, v20
	v_mul_f32_e32 v50, v21, v50
	v_lshlrev_b32_e32 v53, 16, v7
	v_sub_f32_e32 v52, v52, v20
	v_mul_f32_e32 v51, v21, v51
	v_sub_f32_e32 v53, v53, v20
	v_mul_f32_e32 v52, v21, v52
	v_mul_f32_e32 v53, v21, v53
	s_waitcnt lgkmcnt(0)
; #define LAS __attribute__((address_space(3)))
; __device__ __forceinline__ unsigned pk_bf16(float lo, float hi) { unsigned r; asm volatile("v_cvt_pk_bf16_f32 %0, %1, %2" : "=v"(r) : "v"(lo), "v"(hi)); return r; }
; __device__ __forceinline__ float bf_lo(unsigned w) { return __uint_as_float(w << 16); }
; __device__ __forceinline__ float bf_hi(unsigned w) { return __uint_as_float(w & 0xffff0000u); }
; __device__ __forceinline__ void sgu_phase(LAS unsigned char* lds, const bf16* __restrict__ U, const bf16* __restrict__ V, bf16* __restrict__ Y, const bf16* __restrict__ Wm, ...
;     ...
;             {   const float mean = st[2 * srow], rstd = st[2 * srow + 1];
; #pragma unroll
;                 for (int i = 0; i < 4; ++i) { const int cc = (lane >> 4) + 4 * i, col = g * 128 + cc * 8; const u32x4 w = vr[i];
;                     const f32x4 g0 = *(const f32x4*)(ln_g + col), g1 = *(const f32x4*)(ln_g + col + 4), b0 = *(const f32x4*)(ln_b + col), b1 = *(const f32x4*)(ln_b + col + 4);
;                     LAS bf16* vt = VT + (cc * 8) * VTP + srow;
;                     vt[0 * VTP] = (bf16)pk_bf16((bf_lo(w.x) - mean) * rstd * g0.x + b0.x, 0.f); vt[1 * VTP] = (bf16)pk_bf16((bf_hi(w.x) - mean) * rstd * g0.y + b0.y, 0.f);
;                     vt[2 * VTP] = (bf16)pk_bf16((bf_lo(w.y) - mean) * rstd * g0.z + b0.z, 0.f); vt[3 * VTP] = (bf16)pk_bf16((bf_hi(w.y) - mean) * rstd * g0.w + b0.w, 0.f);
;                     vt[4 * VTP] = (bf16)pk_bf16((bf_lo(w.z) - mean) * rstd * g1.x + b1.x, 0.f); vt[5 * VTP] = (bf16)pk_bf16((bf_hi(w.z) - mean) * rstd * g1.y + b1.y, 0.f);
;                     vt[6 * VTP] = (bf16)pk_bf16((bf_lo(w.w) - mean) * rstd * g1.z + b1.z, 0.f); vt[7 * VTP] = (bf16)pk_bf16((bf_hi(w.w) - mean) * rstd * g1.w + b1.w, 0.f); } }
;             __syncthreads();
;             if (gi + 1 < 8) {
; #pragma unroll
;                 for (int i = 0; i < 4; ++i) vr[i] = *(const u32x4*)(V + (size_t)(row0 + srow) * DM + (g + 1) * 128 + ((lane >> 4) + 4 * i) * 8); }
	v_fma_f32 v26, v39, v200, v196
	v_cvt_pk_bf16_f32 v26, v26, v71
	v_fma_f32 v27, v48, v201, v197
	ds_write_b16 v113, v26 offset:9728
	v_cvt_pk_bf16_f32 v26, v27, v71
	v_fma_f32 v28, v49, v202, v198
	ds_write_b16 v113, v26 offset:10000
	v_cvt_pk_bf16_f32 v26, v28, v71
	v_fma_f32 v29, v50, v203, v199
	ds_write_b16 v113, v26 offset:10272
	v_cvt_pk_bf16_f32 v26, v29, v71
	v_fma_f32 v30, v51, v204, v208
	ds_write_b16 v113, v26 offset:10544
	v_cvt_pk_bf16_f32 v26, v30, v71
	v_fma_f32 v31, v52, v205, v209
	ds_write_b16 v113, v26 offset:10816
	v_cvt_pk_bf16_f32 v26, v31, v71
	v_fma_f32 v32, v53, v206, v210
	v_fma_f32 v47, v54, v207, v211
	ds_write_b16 v113, v26 offset:11088
	v_cvt_pk_bf16_f32 v26, v32, v71
	ds_write_b16 v113, v26 offset:11360
	v_cvt_pk_bf16_f32 v38, v47, v71
	v_lshlrev_b32_e32 v39, 16, v8
	v_sub_f32_e32 v39, v39, v20
	v_and_b32_e32 v48, 0xffff0000, v8
	v_mul_f32_e32 v39, v21, v39
	v_lshlrev_b32_e32 v49, 16, v9
	v_sub_f32_e32 v48, v48, v20
	v_and_b32_e32 v50, 0xffff0000, v9
	v_sub_f32_e32 v49, v49, v20
	v_mul_f32_e32 v48, v21, v48
	ds_write_b16 v113, v38 offset:11632
	v_lshlrev_b32_e32 v51, 16, v10
	v_sub_f32_e32 v50, v50, v20
	v_mul_f32_e32 v49, v21, v49
	v_and_b32_e32 v52, 0xffff0000, v10
	v_sub_f32_e32 v51, v51, v20
	v_mul_f32_e32 v50, v21, v50
	v_lshlrev_b32_e32 v53, 16, v11
	v_sub_f32_e32 v52, v52, v20
	v_mul_f32_e32 v51, v21, v51
	v_and_b32_e32 v54, 0xffff0000, v11
	v_sub_f32_e32 v53, v53, v20
	v_mul_f32_e32 v52, v21, v52
	v_sub_f32_e32 v54, v54, v20
	v_mul_f32_e32 v53, v21, v53
	v_mul_f32_e32 v54, v21, v54
	s_waitcnt lgkmcnt(0)
	v_fma_f32 v26, v39, v216, v212
	v_cvt_pk_bf16_f32 v26, v26, v71
	v_fma_f32 v27, v48, v217, v213
	ds_write_b16 v113, v26 offset:18432
	v_cvt_pk_bf16_f32 v26, v27, v71
	v_fma_f32 v28, v49, v218, v214
	ds_write_b16 v113, v26 offset:18704
	v_cvt_pk_bf16_f32 v26, v28, v71
	v_fma_f32 v29, v50, v219, v215
	ds_write_b16 v113, v26 offset:18976
	v_cvt_pk_bf16_f32 v26, v29, v71
	v_fma_f32 v30, v51, v220, v224
	ds_write_b16 v113, v26 offset:19248
	v_cvt_pk_bf16_f32 v26, v30, v71
	v_fma_f32 v31, v52, v221, v225
	ds_write_b16 v113, v26 offset:19520
	v_cvt_pk_bf16_f32 v26, v31, v71
	v_fma_f32 v32, v53, v222, v226
	ds_write_b16 v113, v26 offset:19792
	v_cvt_pk_bf16_f32 v26, v32, v71
	v_fma_f32 v47, v54, v223, v227
	ds_write_b16 v113, v26 offset:20064
	v_cvt_pk_bf16_f32 v38, v47, v71
	s_nop 0
	v_lshlrev_b32_e32 v39, 16, v12
	v_and_b32_e32 v44, 0xffff0000, v12
	v_lshlrev_b32_e32 v45, 16, v13
	v_and_b32_e32 v46, 0xffff0000, v13
	v_lshlrev_b32_e32 v47, 16, v14
	v_and_b32_e32 v48, 0xffff0000, v14
	v_lshlrev_b32_e32 v49, 16, v15
	v_and_b32_e32 v50, 0xffff0000, v15
	v_sub_f32_e32 v39, v39, v20
	v_sub_f32_e32 v44, v44, v20
	v_sub_f32_e32 v45, v45, v20
	v_sub_f32_e32 v46, v46, v20
	v_sub_f32_e32 v47, v47, v20
	v_sub_f32_e32 v48, v48, v20
	v_sub_f32_e32 v49, v49, v20
	v_sub_f32_e32 v20, v50, v20
	v_mul_f32_e32 v39, v21, v39
	v_mul_f32_e32 v20, v21, v20
	v_mul_f32_e32 v44, v21, v44
	v_mul_f32_e32 v45, v21, v45
	v_mul_f32_e32 v46, v21, v46
	v_mul_f32_e32 v47, v21, v47
	v_mul_f32_e32 v48, v21, v48
	v_mul_f32_e32 v49, v21, v49
	ds_write_b16 v113, v38 offset:20336
	s_waitcnt vmcnt(0) lgkmcnt(0)
	v_fma_f32 v21, v39, v232, v228
	v_fma_f32 v26, v44, v233, v229
	v_fma_f32 v25, v20, v239, v243
	v_cvt_pk_bf16_f32 v20, v21, v71
	ds_write_b16 v113, v20 offset:27136
	v_cvt_pk_bf16_f32 v20, v26, v71
	v_fma_f32 v27, v45, v234, v230
	ds_write_b16 v113, v20 offset:27408
	v_cvt_pk_bf16_f32 v20, v27, v71
	v_fma_f32 v29, v46, v235, v231
	ds_write_b16 v113, v20 offset:27680
	v_cvt_pk_bf16_f32 v20, v29, v71
	v_fma_f32 v22, v47, v236, v240
	ds_write_b16 v113, v20 offset:27952
	v_cvt_pk_bf16_f32 v20, v22, v71
	v_fma_f32 v23, v48, v237, v241
	ds_write_b16 v113, v20 offset:28224
	v_cvt_pk_bf16_f32 v20, v23, v71
	v_fma_f32 v24, v49, v238, v242
	ds_write_b16 v113, v20 offset:28496
	v_cvt_pk_bf16_f32 v20, v24, v71
	ds_write_b16 v113, v20 offset:28768
	v_cvt_pk_bf16_f32 v20, v25, v71
	ds_write_b16 v113, v20 offset:29040
	s_waitcnt lgkmcnt(0)
	s_barrier
	s_cbranch_scc1 .LBB0_276
	v_lshl_add_u64 v[0:1], v[86:87], 0, s[8:9]
	v_add_co_u32_e32 v12, vcc, 0x14400000, v0
	s_nop 1
	v_addc_co_u32_e32 v13, vcc, 0, v1, vcc
	flat_load_dwordx4 v[0:3], v[12:13] offset:256
	flat_load_dwordx4 v[4:7], v[12:13] offset:320
	flat_load_dwordx4 v[8:11], v[12:13] offset:384
	s_nop 0
	flat_load_dwordx4 v[12:15], v[12:13] offset:448
